# S5 tile loop: 4th B-multiply MFMA after the first four lane swaps, with the full 12 wait states (8-pass XDL -> VALU) kept between MFMA 2 and the first swap on both paths
# baseline (speedup 1.0000x reference)
.Ls5p_ld:
	global_load_dwordx2 v[190:191], v[232:233], off
	global_load_dwordx2 v[192:193], v[234:235], off
	v_lshl_add_u64 v[232:233], v[232:233], 0, s[50:51]
	v_lshl_add_u64 v[234:235], v[234:235], 0, s[50:51]
	s_nop 4
